# LRUC: last segment (tiles 128..135) gives one tile to each of the 8 waves instead of two tiles to waves 0-3 (tile-index parity mask fixed; explicit wait for the early phase-B loads)
# baseline (speedup 1.0000x reference)
; template <int DIR>
; __device__ __forceinline__ void lru_dir(const bf16_t* XR, const bf16_t* GATE, bf16_t* YP, u32x4* HSF, const bf16_t* bdw_dir, float bias_r, float bias_i, float sp,
;                                         int b, int n2, int lane, int wave, LAS float* xl) {
;     ...
;     for (int seg = 0; seg < 9; ++seg) {
;         f32x16 av[2], bv[2]; float Hl[2], Pl[2]; int trow[2]; bool valid[2];
;         float hloc = 0.f, ploc = 1.f;
; #pragma unroll
;         for (int k = 0; k < 2; ++k) {
;             const int q = seg * 16 + wave * 2 + k; valid[k] = q < 136;
;             const int T = DIR == 0 ? q : (q < 8 ? 7 - q : 143 - q);
;             trow[k] = T < 8 ? ML + b * CTXL + 32 * T : b * SEQ + 32 * (T - 8);
;             if (valid[k]) {
.LBB0_22:
	s_cmpk_lg_i32 s39, 0x1000
	s_cbranch_scc1 .Lseg8a_skip
	s_lshr_b32 s98, s22, 1
	s_sub_i32 s38, s38, s98
	s_lshl_b32 s98, s22, 4
	s_sub_i32 s25, s25, s98
	s_sub_i32 s37, s37, s98
	v_subrev_u32_e32 v103, s98, v103

; template <int DIR>
; __device__ __forceinline__ void lru_dir(const bf16_t* XR, const bf16_t* GATE, bf16_t* YP, u32x4* HSF, const bf16_t* bdw_dir, float bias_r, float bias_i, float sp,
;                                         int b, int n2, int lane, int wave, LAS float* xl) {
;     ...
;         for (int k = 0; k < 2; ++k) {
;             const int q = seg * 16 + wave * 2 + k; valid[k] = q < 136;
;             const int T = DIR == 0 ? q : (q < 8 ? 7 - q : 143 - q);
;             trow[k] = T < 8 ? ML + b * CTXL + 32 * T : b * SEQ + 32 * (T - 8);
;             if (valid[k]) {
;     ...
;             float H = 0.f, P = 1.f;
; #pragma unroll
;             for (int rr = 0; rr < 16; ++rr) { const int r = DIR == 0 ? rr : 15 - rr; H = av[k][r] * H + bv[k][r]; P *= av[k][r]; }
;             Hl[k] = H; Pl[k] = P;
;             const float val = H + P * hloc, got = __shfl_xor(val, 32);
;             const float st2 = first ? hloc : got;
;             const float endv = H + P * st2, got2 = __shfl_xor(endv, 32);
;             hloc = first ? got2 : endv;
;             ploc *= P * __shfl_xor(P, 32);
;         }
.LBB0_27:
	v_fma_f32 v0, 0, v124, v122
	v_fma_f32 v0, v125, v0, v123
	v_mul_f32_e32 v1, v124, v125
	v_fma_f32 v0, v128, v0, v126
	v_mul_f32_e32 v1, v128, v1
	v_fma_f32 v0, v129, v0, v127
	v_mul_f32_e32 v1, v129, v1
	v_fma_f32 v0, v132, v0, v130
	v_mul_f32_e32 v1, v132, v1
	v_fma_f32 v0, v133, v0, v131
	v_mul_f32_e32 v1, v133, v1
	v_fma_f32 v0, v136, v0, v134
	v_mul_f32_e32 v1, v136, v1
	v_fma_f32 v0, v137, v0, v135
	v_mul_f32_e32 v1, v137, v1
	v_fma_f32 v0, v140, v0, v138
	v_mul_f32_e32 v1, v140, v1
	v_fma_f32 v0, v141, v0, v139
	v_mul_f32_e32 v1, v141, v1
	v_fma_f32 v0, v144, v0, v142
	v_mul_f32_e32 v1, v144, v1
	v_fma_f32 v0, v145, v0, v143
	v_mul_f32_e32 v1, v145, v1
	v_fma_f32 v0, v148, v0, v146
	v_mul_f32_e32 v1, v148, v1
	v_fma_f32 v0, v149, v0, v147
	v_mul_f32_e32 v1, v149, v1
	v_fma_f32 v0, v152, v0, v150
	v_mul_f32_e32 v1, v152, v1
	v_fma_f32 v48, v153, v0, v151
	v_mul_f32_e32 v109, v153, v1
	v_fma_f32 v0, 0, v109, v48
	ds_bpermute_b32 v0, v176, v0
	ds_bpermute_b32 v98, v176, v109
	s_add_i32 s6, s38, 1
	s_cmpk_eq_i32 s39, 0x1000
	s_cselect_b32 s6, 0x88, s6
	s_cmpk_lt_i32 s6, 0x88
	s_cselect_b64 s[2:3], -1, 0
	s_waitcnt lgkmcnt(1)
	v_cndmask_b32_e64 v0, v0, 0, s[40:41]
	v_fma_f32 v100, v0, v109, v48
	ds_bpermute_b32 v99, v176, v100
	s_cmp_lt_i32 s6, 8
	s_cselect_b32 s63, s31, s29
	s_mov_b64 s[6:7], -1
	s_and_b64 vcc, exec, s[2:3]
	s_cbranch_vccnz .LBB0_29
	s_mov_b64 s[6:7], 0

; __device__ __forceinline__ unsigned pk2(float lo, float hi) { unsigned r; asm("v_cvt_pk_bf16_f32 %0, %1, %2" : "=v"(r) : "v"(lo), "v"(hi)); return r; }
; template <int DIR>
; __device__ __forceinline__ void lru_dir(const bf16_t* XR, const bf16_t* GATE, bf16_t* YP, u32x4* HSF, const bf16_t* bdw_dir, float bias_r, float bias_i, float sp,
;                                         int b, int n2, int lane, int wave, LAS float* xl) {
;     ...
;                 const int tg = trow[k] < ML ? (trow[k] >> 12) * 136 + 8 + ((trow[k] & (SEQ - 1)) >> 5) : b * 136 + ((trow[k] - ML - b * CTXL) >> 5);
;                 u32x4* hp = HSF + (((size_t)tg * 32 + n2) * 64 + lane) * 2;
;                 if (DIR == 0) {
;                     u32x4 w0, w1;
;                     w0.x = pk2(hs[0], hs[1]); w0.y = pk2(hs[2], hs[3]); w0.z = pk2(hs[4], hs[5]); w0.w = pk2(hs[6], hs[7]);
;                     w1.x = pk2(hs[8], hs[9]); w1.y = pk2(hs[10], hs[11]); w1.z = pk2(hs[12], hs[13]); w1.w = pk2(hs[14], hs[15]);
;                     hp[0] = w0; hp[1] = w1;
.LBB0_37:
	s_andn2_b64 vcc, exec, s[10:11]
	s_cbranch_vccnz .LBB0_39
	s_ashr_i32 s6, s7, 12
	s_lshr_b32 s7, s7, 5
	s_mulk_i32 s6, 0x88
	s_and_b32 s7, s7, 0x7f
	s_add_i32 s6, s6, s7
	s_add_i32 s6, s6, 8

; template <int DIR>
; __device__ __forceinline__ void lru_dir(const bf16_t* XR, const bf16_t* GATE, bf16_t* YP, u32x4* HSF, const bf16_t* bdw_dir, float bias_r, float bias_i, float sp,
;                                         int b, int n2, int lane, int wave, LAS float* xl) {
;     ...
;     bf16x8 Br[4], Bi[4];
;     const bf16_t* wrp = bdw_dir + (size_t)n * 4096 + (half * 32 + e) * 64 + 8 * hh;
;     const bf16_t* wip = wrp + 16 * 4096;
; #pragma unroll
;     for (int kk = 0; kk < 4; ++kk) { Br[kk] = *(const bf16x8*)(wrp + 16 * kk); Bi[kk] = *(const bf16x8*)(wip + 16 * kk); }
;     bf16x8 I0, I1;
; #pragma unroll
;     for (int jj = 0; jj < 8; ++jj) { I0[jj] = (8 * hh + jj == e) ? (short)0x3F80 : (short)0; I1[jj] = (16 + 8 * hh + jj == e) ? (short)0x3F80 : (short)0; }
;     const bool first = (hh == DIR);
;     const int chcol = n * 64 + half * 32;
;     const float spm = -8.0f * 1.4426950408889634f * sp;
; __device__ __forceinline__ void lru_block_phase(const bf16_t* XR, const bf16_t* GATE, bf16_t* YP, u32x4* HSF, const bf16_t* bdw_j, const float* ga_b, const float* gx_b, const float* lam,
;                                                 LAS unsigned char* lds, int lane, int wave, int G) {
;     ...
;         __syncthreads();
;         { const float bias_r = ga_b[DM + ch], bias_i = gx_b[DM + ch], sp = log1pf(__expf(-lam[DM + ch]));
;           lru_dir<1>(XR, GATE, YP, HSF, bdw_j + 2 * 16 * 4096, bias_r, bias_i, sp, b, n2, lane, wave, xl); }
.LBB0_45:
	s_lshl_b32 s98, s22, 4
	s_add_i32 s25, s25, s98
	s_add_i32 s37, s37, s98
	v_add_u32_e32 v103, s98, v103
	v_mov_b32_e32 v0, 0x1000
	v_lshl_or_b32 v1, v111, 2, v0
	s_barrier
	global_load_dword v0, v1, s[70:71]
	global_load_dword v114, v1, s[66:67]
	global_load_dword v116, v1, s[68:69]
	s_lshl_b32 s2, s19, 1
	s_add_u32 s2, s23, s2
	s_addc_u32 s3, s24, 0
	s_lshl_b32 s6, s35, 5
	v_or_b32_e32 v1, s6, v172
	v_lshlrev_b32_e32 v48, 7, v1
	v_mov_b32_e32 v111, v49
	v_lshl_add_u64 v[2:3], s[2:3], 0, v[48:49]
	v_lshl_add_u64 v[2:3], v[2:3], 0, v[110:111]
	s_mov_b32 s2, 0x20000
	v_add_co_u32_e32 v4, vcc, s2, v2
	s_mov_b32 s2, 0x3f2aaaab
	s_nop 0
	v_addc_co_u32_e32 v5, vcc, 0, v3, vcc
	global_load_dwordx4 v[66:69], v[2:3], off
	global_load_dwordx4 v[70:73], v[2:3], off offset:32
	global_load_dwordx4 v[74:77], v[2:3], off offset:64
	global_load_dwordx4 v[78:81], v[2:3], off offset:96
	global_load_dwordx4 v[82:85], v[4:5], off
	global_load_dwordx4 v[86:89], v[4:5], off offset:32
	global_load_dwordx4 v[90:93], v[4:5], off offset:64
	global_load_dwordx4 v[94:97], v[4:5], off offset:96
	s_or_b32 s6, s36, s6
	s_mov_b32 s7, s77
	s_lshl_b32 s6, s6, 1
	s_mov_b32 s18, 0
	v_mov_b32_e32 v101, 0
	s_mov_b32 s19, s28
	v_lshl_add_u64 v[118:119], s[8:9], 0, v[110:111]
	v_lshl_add_u64 v[120:121], v[104:105], 0, s[6:7]
	v_lshl_add_u64 v[122:123], v[106:107], 0, s[6:7]
	s_mov_b32 s35, s22
	s_waitcnt vmcnt(10)
	v_mul_f32_e32 v0, 0xbfb8aa3b, v0
	v_exp_f32_e32 v14, v0
	s_waitcnt vmcnt(9)
	v_mov_b32_e32 v115, v114
	s_waitcnt vmcnt(8)
	v_mov_b32_e32 v117, v116
	v_add_f32_e32 v2, 1.0, v14
	v_add_f32_e32 v3, -1.0, v2
	v_frexp_mant_f32_e32 v4, v2
	v_cvt_f64_f32_e32 v[0:1], v2
	v_sub_f32_e32 v5, v3, v2
	v_frexp_exp_i32_f64_e32 v0, v[0:1]
	v_cmp_gt_f32_e32 vcc, s2, v4
	v_sub_f32_e32 v3, v14, v3
	v_add_f32_e32 v1, 1.0, v5
	v_subbrev_co_u32_e32 v0, vcc, 0, v0, vcc
	v_add_f32_e32 v1, v3, v1
	v_sub_u32_e32 v3, 0, v0
	v_ldexp_f32 v2, v2, v3
	v_add_f32_e32 v4, -1.0, v2
	v_add_f32_e32 v5, 1.0, v2
	v_ldexp_f32 v1, v1, v3
	v_add_f32_e32 v3, 1.0, v4
	v_add_f32_e32 v6, -1.0, v5
	v_sub_f32_e32 v3, v2, v3
	v_sub_f32_e32 v2, v2, v6
	v_add_f32_e32 v6, v1, v3
	v_add_f32_e32 v1, v1, v2
	v_add_f32_e32 v8, v5, v1
	v_rcp_f32_e32 v9, v8
	v_add_f32_e32 v3, v4, v6
	v_sub_f32_e32 v4, v3, v4
	v_sub_f32_e32 v2, v8, v5
	v_mul_f32_e32 v11, v3, v9
	v_sub_f32_e32 v10, v6, v4
	v_mul_f32_e32 v4, v8, v11
	v_sub_f32_e32 v1, v1, v2
	v_fma_f32 v6, v11, v8, -v4
	v_fmac_f32_e32 v6, v11, v1
	v_add_f32_e32 v2, v4, v6
	v_sub_f32_e32 v5, v3, v2
	v_mov_b32_e32 v7, v2
	v_pk_add_f32 v[2:3], v[2:3], v[4:5] neg_lo:[0,1] neg_hi:[0,1]
	v_cvt_f32_i32_e32 v0, v0
	v_pk_add_f32 v[2:3], v[2:3], v[6:7] neg_lo:[0,1] neg_hi:[0,1]
	s_mov_b32 s2, 0x3f317218
	v_add_f32_e32 v3, v10, v3
	v_add_f32_e32 v2, v2, v3
	v_add_f32_e32 v3, v5, v2
	v_mul_f32_e32 v7, v9, v3
	v_mul_f32_e32 v4, v8, v7
	v_sub_f32_e32 v5, v5, v3
	v_add_f32_e32 v12, v11, v7
	v_fma_f32 v6, v7, v8, -v4
	v_add_f32_e32 v10, v2, v5
	v_sub_f32_e32 v2, v12, v11
	v_fmac_f32_e32 v6, v7, v1
	v_sub_f32_e32 v1, v7, v2
	v_add_f32_e32 v2, v4, v6
	v_sub_f32_e32 v5, v3, v2
	v_mov_b32_e32 v7, v2
	v_pk_add_f32 v[2:3], v[2:3], v[4:5] neg_lo:[0,1] neg_hi:[0,1]
	s_nop 0
	v_pk_add_f32 v[2:3], v[2:3], v[6:7] neg_lo:[0,1] neg_hi:[0,1]
	s_nop 0
	v_add_f32_e32 v3, v10, v3
	v_add_f32_e32 v2, v2, v3
	v_add_f32_e32 v2, v5, v2
	v_mul_f32_e32 v2, v9, v2
	v_add_f32_e32 v1, v1, v2
	v_add_f32_e32 v2, v12, v1
	v_mul_f32_e32 v4, v2, v2
	v_sub_f32_e32 v5, v2, v12
	v_fmamk_f32 v6, v4, 0x3e9b6dac, v221
	v_sub_f32_e32 v5, v1, v5
	v_mul_f32_e32 v1, v2, v4
	v_fmaak_f32 v175, v4, v6, 0x3f2aaada
	v_ldexp_f32 v7, v5, 1
	v_pk_mul_f32 v[4:5], v[0:1], v[174:175]
	v_ldexp_f32 v3, v2, 1
	v_fma_f32 v2, v0, s2, -v4
	v_fmac_f32_e32 v2, 0xb102e308, v0
	v_pk_add_f32 v[0:1], v[4:5], v[2:3]
	v_mov_b32_e32 v6, v4
	v_sub_f32_e32 v10, v1, v3
	v_pk_add_f32 v[8:9], v[0:1], v[4:5] neg_lo:[0,1] neg_hi:[0,1]
	v_sub_f32_e32 v4, v5, v10
	v_add_f32_e32 v7, v7, v4
	v_pk_add_f32 v[4:5], v[0:1], v[6:7]
	v_mov_b32_e32 v3, v0
	v_mov_b32_e32 v9, v5
	v_pk_add_f32 v[12:13], v[2:3], v[8:9] neg_lo:[0,1] neg_hi:[0,1]
	v_pk_add_f32 v[2:3], v[2:3], v[8:9]
	v_mov_b32_e32 v11, v0
	v_pk_add_f32 v[8:9], v[2:3], v[0:1] op_sel:[1,0] op_sel_hi:[0,1] neg_lo:[0,1] neg_hi:[0,1]
	v_mov_b32_e32 v10, v7
	v_mov_b32_e32 v6, v5
	v_mov_b32_e32 v7, v3
	v_pk_mov_b32 v[0:1], v[0:1], v[8:9] op_sel:[1,0]
	v_pk_add_f32 v[4:5], v[4:5], v[8:9] op_sel_hi:[1,0] neg_lo:[0,1] neg_hi:[0,1]
	v_pk_add_f32 v[0:1], v[6:7], v[0:1] neg_lo:[0,1] neg_hi:[0,1]
	v_mov_b32_e32 v4, v12
	v_pk_add_f32 v[0:1], v[10:11], v[0:1] neg_lo:[0,1] neg_hi:[0,1]
	v_mov_b32_e32 v13, v3
	v_pk_add_f32 v[4:5], v[4:5], v[0:1]
	s_mov_b32 s2, 0x7f800000
	v_pk_add_f32 v[6:7], v[4:5], v[4:5] op_sel:[0,1] op_sel_hi:[1,0]
	v_cmp_neq_f32_e32 vcc, s2, v14
	v_pk_add_f32 v[2:3], v[2:3], v[6:7] op_sel:[1,0] op_sel_hi:[0,1]
	v_mov_b32_e32 v5, v2
	v_mov_b32_e32 v1, v6
	v_pk_add_f32 v[6:7], v[4:5], v[12:13] neg_lo:[0,1] neg_hi:[0,1]
	s_mov_b32 s2, 0x33800000
	v_sub_f32_e32 v3, v4, v6
	v_pk_add_f32 v[0:1], v[0:1], v[6:7] neg_lo:[0,1] neg_hi:[0,1]
	v_sub_f32_e32 v3, v12, v3
	v_add_f32_e32 v0, v0, v3
	v_add_f32_e32 v0, v0, v1
	v_add_f32_e32 v0, v2, v0
	v_cndmask_b32_e32 v0, v249, v0, vcc
	v_cmp_ngt_f32_e32 vcc, -1.0, v14
	s_nop 1
	v_cndmask_b32_e32 v0, v250, v0, vcc
	v_cmp_neq_f32_e32 vcc, -1.0, v14
	s_nop 1
	v_cndmask_b32_e32 v0, v251, v0, vcc
	v_cmp_lt_f32_e64 vcc, |v14|, s2
	s_nop 1
	v_cndmask_b32_e32 v0, v0, v14, vcc
	v_mul_f32_e32 v124, 0xc138aa3b, v0
	v_mov_b32_e32 v125, v124
	s_branch .LBB0_48

; template <int DIR>
; __device__ __forceinline__ void lru_dir(const bf16_t* XR, const bf16_t* GATE, bf16_t* YP, u32x4* HSF, const bf16_t* bdw_dir, float bias_r, float bias_i, float sp,
;                                         int b, int n2, int lane, int wave, LAS float* xl) {
;     ...
;         for (int k = 0; k < 2; ++k) {
;             const int q = seg * 16 + wave * 2 + k; valid[k] = q < 136;
;             const int T = DIR == 0 ? q : (q < 8 ? 7 - q : 143 - q);
;             trow[k] = T < 8 ? ML + b * CTXL + 32 * T : b * SEQ + 32 * (T - 8);
;             if (valid[k]) {
.LBB0_48:
	s_cmpk_lg_i32 s18, 0x40
	s_cbranch_scc1 .Lseg8b_skip
	s_lshr_b32 s98, s22, 1
	s_sub_i32 s35, s35, s98
	s_add_i32 s19, s19, s98

; __device__ __forceinline__ f32x16 mfma32(bf16x8 a, bf16x8 b, f32x16 c) { return __builtin_amdgcn_mfma_f32_32x32x16_bf16(a, b, c, 0, 0, 0); }
; template <int DIR>
; __device__ __forceinline__ void lru_dir(const bf16_t* XR, const bf16_t* GATE, bf16_t* YP, u32x4* HSF, const bf16_t* bdw_dir, float bias_r, float bias_i, float sp,
;                                         int b, int n2, int lane, int wave, LAS float* xl) {
;     ...
;         for (int k = 0; k < 2; ++k) {
;             const int q = seg * 16 + wave * 2 + k; valid[k] = q < 136;
;             const int T = DIR == 0 ? q : (q < 8 ? 7 - q : 143 - q);
;             trow[k] = T < 8 ? ML + b * CTXL + 32 * T : b * SEQ + 32 * (T - 8);
;             if (valid[k]) {
;                 const bf16_t* ap = XR + (size_t)(trow[k] + tau) * DM + n * 64 + 8 * hh;
;                 bf16x8 A[4];
; #pragma unroll
;                 for (int kk = 0; kk < 4; ++kk) A[kk] = *(const bf16x8*)(ap + 16 * kk);
;                 f32x16 ar, ai, xv;
; #pragma unroll
;                 for (int r = 0; r < 16; ++r) { ar[r] = 0.f; ai[r] = 0.f; xv[r] = 0.f; }
; #pragma unroll
;                 for (int kk = 0; kk < 4; ++kk) { ar = mfma32(A[kk], Br[kk], ar); ai = mfma32(A[kk], Bi[kk], ai); }
;                 const bf16x8 Ax0 = half ? A[2] : A[0], Ax1 = half ? A[3] : A[1];
;                 xv = mfma32(Ax0, I0, xv); xv = mfma32(Ax1, I1, xv);
;     ...
;             float H = 0.f, P = 1.f;
; #pragma unroll
;             for (int rr = 0; rr < 16; ++rr) { const int r = DIR == 0 ? rr : 15 - rr; H = av[k][r] * H + bv[k][r]; P *= av[k][r]; }
;             Hl[k] = H; Pl[k] = P;
;             const float val = H + P * hloc, got = __shfl_xor(val, 32);
;             const float st2 = first ? hloc : got;
;             const float endv = H + P * st2, got2 = __shfl_xor(endv, 32);
;             hloc = first ? got2 : endv;
;             ploc *= P * __shfl_xor(P, 32);
;         }
.LBB0_50:
	s_nop 0
	v_fma_f32 v0, 0, v169, v151
	v_fma_f32 v0, v168, v0, v150
	v_mul_f32_e32 v1, v169, v168
	v_fma_f32 v0, v167, v0, v149
	v_mul_f32_e32 v1, v167, v1
	v_fma_f32 v0, v166, v0, v148
	v_mul_f32_e32 v1, v166, v1
	v_fma_f32 v0, v165, v0, v147
	v_mul_f32_e32 v1, v165, v1
	v_fma_f32 v0, v164, v0, v146
	v_mul_f32_e32 v1, v164, v1
	v_fma_f32 v0, v163, v0, v131
	v_mul_f32_e32 v1, v163, v1
	v_fma_f32 v0, v162, v0, v130
	v_mul_f32_e32 v1, v162, v1
	v_fma_f32 v0, v159, v0, v129
	v_mul_f32_e32 v1, v159, v1
	v_fma_f32 v0, v158, v0, v128
	v_mul_f32_e32 v1, v158, v1
	v_fma_f32 v0, v157, v0, v137
	v_mul_f32_e32 v1, v157, v1
	v_fma_f32 v0, v156, v0, v136
	v_mul_f32_e32 v1, v156, v1
	v_fma_f32 v0, v153, v0, v135
	v_mul_f32_e32 v1, v153, v1
	v_fma_f32 v0, v152, v0, v134
	v_mul_f32_e32 v1, v152, v1
	v_fma_f32 v0, v141, v0, v139
	v_mul_f32_e32 v1, v141, v1
	v_fma_f32 v111, v140, v0, v138
	v_mul_f32_e32 v175, v140, v1
	v_fma_f32 v0, 0, v175, v111
	ds_bpermute_b32 v0, v176, v0
	s_add_i32 s2, s35, 1
	s_cmpk_eq_i32 s18, 0x40
	s_cselect_b32 s2, 0x88, s2
	s_cmpk_lt_i32 s2, 0x88
	s_cselect_b64 s[10:11], -1, 0
	s_cmp_lt_i32 s35, 7
	s_cselect_b32 s3, 7, 0x8f
	s_add_i32 s3, s3, s19
	s_waitcnt lgkmcnt(0)
	v_cndmask_b32_e64 v0, 0, v0, s[40:41]
	s_add_i32 s3, s3, -1
	v_fma_f32 v48, v0, v175, v111
	s_lshl_b32 s6, s3, 5
	ds_bpermute_b32 v99, v176, v48
	ds_bpermute_b32 v98, v176, v175
	s_cmp_lt_i32 s3, 8
	s_cselect_b32 s37, s31, s29
	s_add_i32 s37, s37, s6
	v_or_b32_e32 v144, s37, v173
	v_mov_b32_e32 v154, 0
	s_cmpk_gt_i32 s2, 0x87
	v_ashrrev_i32_e32 v145, 31, v144
	v_mov_b32_e32 v155, 0
	v_mov_b32_e32 v142, 0
	v_mov_b32_e32 v143, 0
	v_mov_b32_e32 v34, 0
	v_mov_b32_e32 v35, 0
	v_mov_b32_e32 v32, 0
	v_mov_b32_e32 v33, 0
	v_mov_b32_e32 v24, 0
	v_mov_b32_e32 v25, 0
	v_mov_b32_e32 v26, 0
	v_mov_b32_e32 v27, 0
	v_mov_b32_e32 v28, 0
	v_mov_b32_e32 v29, 0
	v_mov_b32_e32 v30, 0
	v_mov_b32_e32 v31, 0
	v_mov_b32_e32 v127, 1.0
	v_mov_b32_e32 v160, 1.0
	v_mov_b32_e32 v161, 1.0
	v_mov_b32_e32 v36, 1.0
	v_mov_b32_e32 v37, 1.0
	v_mov_b32_e32 v38, 1.0
	v_mov_b32_e32 v39, 1.0
	v_mov_b32_e32 v40, 1.0
	v_mov_b32_e32 v41, 1.0
	v_mov_b32_e32 v42, 1.0
	v_mov_b32_e32 v43, 1.0
	v_mov_b32_e32 v44, 1.0
	v_mov_b32_e32 v45, 1.0
	v_mov_b32_e32 v46, 1.0
	v_mov_b32_e32 v47, 1.0
	s_cbranch_scc1 .LBB0_52
	v_lshlrev_b64 v[0:1], 11, v[144:145]
	v_lshl_add_u64 v[12:13], v[118:119], 0, v[0:1]
	global_load_dwordx4 v[0:3], v[12:13], off
	global_load_dwordx4 v[4:7], v[12:13], off offset:32
	global_load_dwordx4 v[8:11], v[12:13], off offset:64
	s_nop 0
	global_load_dwordx4 v[12:15], v[12:13], off offset:96
	s_ashr_i32 s98, s37, 12
	s_mulk_i32 s98, 0x88
	s_lshr_b32 s99, s37, 5
	s_and_b32 s99, s99, 0x7e
	s_add_i32 s98, s98, s99
	s_add_i32 s98, s98, 8
	s_sub_i32 s99, s37, s30
	s_addk_i32 s99, 0x8000
	s_ashr_i32 s99, s99, 5
	s_add_i32 s99, s99, s34
	s_cmp_lt_i32 s37, 0x8000
	s_cselect_b32 s98, s98, s99
	s_ashr_i32 s99, s98, 31
	s_lshl_b64 s[98:99], s[98:99], 16
	v_lshl_add_u64 v[216:217], v[112:113], 0, s[98:99]
	v_lshlrev_b64 v[218:219], 11, v[144:145]
	global_load_dwordx4 v[200:203], v[216:217], off offset:16
	global_load_dwordx4 v[204:207], v[216:217], off
	v_lshl_add_u64 v[218:219], v[120:121], 0, v[218:219]
	s_nop 0
	global_load_dwordx4 v[208:211], v[218:219], off
	global_load_dwordx4 v[212:215], v[218:219], off offset:32
	s_waitcnt vmcnt(7)
	v_mfma_f32_32x32x16_bf16 v[32:47], v[0:3], v[66:69], 0
	s_waitcnt vmcnt(4)
	v_cndmask_b32_e64 v183, v15, v7, s[56:57]
	v_cndmask_b32_e64 v182, v14, v6, s[56:57]
	v_cndmask_b32_e64 v181, v13, v5, s[56:57]
	v_cndmask_b32_e64 v180, v12, v4, s[56:57]
	v_mfma_f32_32x32x16_bf16 v[32:47], v[4:7], v[70:73], v[32:47]
	v_mfma_f32_32x32x16_bf16 v[16:31], v[0:3], v[82:85], 0
	v_cndmask_b32_e64 v3, v11, v3, s[56:57]
	v_cndmask_b32_e64 v2, v10, v2, s[56:57]
	v_cndmask_b32_e64 v1, v9, v1, s[56:57]
	v_cndmask_b32_e64 v0, v8, v0, s[56:57]
	v_mfma_f32_32x32x16_bf16 v[32:47], v[8:11], v[74:77], v[32:47]
	v_mfma_f32_32x32x16_bf16 v[16:31], v[4:7], v[86:89], v[16:31]
	v_mfma_f32_32x32x16_bf16 v[32:47], v[12:15], v[78:81], v[32:47]
	v_mfma_f32_32x32x16_bf16 v[16:31], v[8:11], v[90:93], v[16:31]
	s_nop 10
	v_add_f32_e64 v32, v114, v32
	v_add_f32_e64 v33, v115, v33
	v_mul_f32_e64 v32, v32, s14
	v_mul_f32_e64 v33, v33, s14
	v_exp_f32_e32 v32, v32
	v_exp_f32_e32 v33, v33
	v_mfma_f32_32x32x16_bf16 v[16:31], v[12:15], v[94:97], v[16:31]
	v_add_f32_e64 v32, v32, 1.0
	v_add_f32_e64 v33, v33, 1.0
	v_rcp_f32_e32 v32, v32
	v_rcp_f32_e32 v33, v33
	s_nop 0
	v_pk_mul_f32 v[32:33], v[124:125], v[32:33]
	v_mfma_f32_32x32x16_bf16 v[0:15], v[0:3], v[58:61], 0
	s_nop 4
	v_add_f32_e64 v16, v116, v16
	v_add_f32_e64 v17, v117, v17
	v_exp_f32_e32 v126, v32
	v_pk_mul_f32 v[16:17], v[16:17], s[14:15] op_sel_hi:[1,0]
	v_exp_f32_e32 v127, v33
	v_exp_f32_e32 v16, v16
	v_exp_f32_e32 v17, v17
	v_pk_fma_f32 v[32:33], v[126:127], v[126:127], 1.0 op_sel_hi:[1,1,0] neg_lo:[1,0,0] neg_hi:[1,0,0]
	v_mfma_f32_32x32x16_bf16 v[0:15], v[180:183], v[62:65], v[0:15]
	v_add_f32_e64 v16, v16, 1.0
	v_add_f32_e64 v17, v17, 1.0
	v_max_f32_e32 v33, 0, v33
	v_max_f32_e32 v32, 0, v32
	v_rcp_f32_e32 v16, v16
	v_rcp_f32_e32 v17, v17
	v_sqrt_f32_e32 v32, v32
	v_sqrt_f32_e32 v33, v33
	s_nop 0
	v_pk_mul_f32 v[16:17], v[16:17], v[32:33]
	s_nop 1
	v_pk_mul_f32 v[154:155], v[0:1], v[16:17]
	v_pk_add_f32 v[0:1], v[114:115], v[34:35]
	v_pk_add_f32 v[16:17], v[116:117], v[18:19]
	v_pk_mul_f32 v[0:1], v[0:1], s[14:15] op_sel_hi:[1,0]
	v_pk_mul_f32 v[16:17], v[16:17], s[14:15] op_sel_hi:[1,0]
	v_exp_f32_e32 v0, v0
	v_exp_f32_e32 v1, v1
	v_exp_f32_e32 v16, v16
	v_exp_f32_e32 v17, v17
	v_pk_add_f32 v[0:1], v[0:1], 1.0 op_sel_hi:[1,0]
	s_nop 0
; template <int DIR>
; __device__ __forceinline__ void lru_dir(const bf16_t* XR, const bf16_t* GATE, bf16_t* YP, u32x4* HSF, const bf16_t* bdw_dir, float bias_r, float bias_i, float sp,
;                                         int b, int n2, int lane, int wave, LAS float* xl) {
;     ...
; #pragma unroll
;                 for (int r = 0; r < 16; r += 2) {
;                     const f32x2 er = ((f32x2){ar[r], ar[r + 1]} + bias_r) * -1.4426950408889634f, ei = ((f32x2){ai[r], ai[r + 1]} + bias_i) * -1.4426950408889634f;
;                     const f32x2 dr = (f32x2){__builtin_amdgcn_exp2f(er[0]), __builtin_amdgcn_exp2f(er[1])} + 1.0f, di = (f32x2){__builtin_amdgcn_exp2f(ei[0]), __builtin_amdgcn_exp2f(ei[1])} + 1.0f;
;                     const f32x2 rg = {__builtin_amdgcn_rcpf(dr[0]), __builtin_amdgcn_rcpf(dr[1])}, ig = {__builtin_amdgcn_rcpf(di[0]), __builtin_amdgcn_rcpf(di[1])};
;                     const f32x2 la = rg * spm;
;                     const f32x2 aa = {__builtin_amdgcn_exp2f(la[0]), __builtin_amdgcn_exp2f(la[1])};
;                     const f32x2 om = __builtin_elementwise_max(1.0f - aa * aa, (f32x2){0.f, 0.f});
;                     const f32x2 bb = (f32x2){__builtin_amdgcn_sqrtf(om[0]), __builtin_amdgcn_sqrtf(om[1])} * ig * (f32x2){xv[r], xv[r + 1]};
;                     av[k][r] = aa[0]; av[k][r + 1] = aa[1]; bv[k][r] = bb[0]; bv[k][r + 1] = bb[1];
;                 }
	v_rcp_f32_e32 v0, v0
	v_rcp_f32_e32 v1, v1
	v_pk_add_f32 v[16:17], v[16:17], 1.0 op_sel_hi:[1,0]
	v_pk_mul_f32 v[0:1], v[124:125], v[0:1]
	s_nop 0
	v_exp_f32_e32 v160, v0
	v_exp_f32_e32 v161, v1
	v_rcp_f32_e32 v16, v16
	v_rcp_f32_e32 v17, v17
	v_pk_fma_f32 v[0:1], v[160:161], v[160:161], 1.0 op_sel_hi:[1,1,0] neg_lo:[1,0,0] neg_hi:[1,0,0]
	s_nop 0
	v_max_f32_e32 v1, 0, v1
	v_max_f32_e32 v0, 0, v0
	v_sqrt_f32_e32 v0, v0
	v_sqrt_f32_e32 v1, v1
	s_nop 0
	v_pk_mul_f32 v[0:1], v[16:17], v[0:1]
	s_nop 0
	v_pk_mul_f32 v[142:143], v[2:3], v[0:1]
	v_pk_add_f32 v[0:1], v[114:115], v[36:37]
	v_pk_add_f32 v[2:3], v[116:117], v[20:21]
	v_pk_mul_f32 v[0:1], v[0:1], s[14:15] op_sel_hi:[1,0]
	v_pk_mul_f32 v[2:3], v[2:3], s[14:15] op_sel_hi:[1,0]
	v_exp_f32_e32 v0, v0
	v_exp_f32_e32 v1, v1
	v_exp_f32_e32 v2, v2
	v_exp_f32_e32 v3, v3
	v_pk_add_f32 v[0:1], v[0:1], 1.0 op_sel_hi:[1,0]
	s_nop 0
	v_rcp_f32_e32 v0, v0
	v_rcp_f32_e32 v1, v1
	v_pk_add_f32 v[2:3], v[2:3], 1.0 op_sel_hi:[1,0]
	v_pk_mul_f32 v[0:1], v[124:125], v[0:1]
	s_nop 0
	v_exp_f32_e32 v36, v0
	v_exp_f32_e32 v37, v1
	v_rcp_f32_e32 v2, v2
	v_rcp_f32_e32 v3, v3
	v_pk_fma_f32 v[0:1], v[36:37], v[36:37], 1.0 op_sel_hi:[1,1,0] neg_lo:[1,0,0] neg_hi:[1,0,0]
	s_nop 0
	v_max_f32_e32 v1, 0, v1
	v_max_f32_e32 v0, 0, v0
	v_sqrt_f32_e32 v0, v0
	v_sqrt_f32_e32 v1, v1
	s_nop 0
	v_pk_mul_f32 v[0:1], v[2:3], v[0:1]
	s_nop 0
	v_pk_mul_f32 v[34:35], v[4:5], v[0:1]
	v_pk_add_f32 v[0:1], v[114:115], v[38:39]
	v_pk_add_f32 v[2:3], v[116:117], v[22:23]
	v_pk_mul_f32 v[0:1], v[0:1], s[14:15] op_sel_hi:[1,0]
	v_pk_mul_f32 v[2:3], v[2:3], s[14:15] op_sel_hi:[1,0]
	v_exp_f32_e32 v0, v0
	v_exp_f32_e32 v1, v1
	v_exp_f32_e32 v2, v2
	v_exp_f32_e32 v3, v3
	v_pk_add_f32 v[0:1], v[0:1], 1.0 op_sel_hi:[1,0]
	s_nop 0
	v_rcp_f32_e32 v0, v0
	v_rcp_f32_e32 v1, v1
	v_pk_add_f32 v[2:3], v[2:3], 1.0 op_sel_hi:[1,0]
	v_pk_mul_f32 v[0:1], v[124:125], v[0:1]
	s_nop 0
	v_exp_f32_e32 v38, v0
	v_exp_f32_e32 v39, v1
	v_rcp_f32_e32 v2, v2
	v_rcp_f32_e32 v3, v3
	v_pk_fma_f32 v[0:1], v[38:39], v[38:39], 1.0 op_sel_hi:[1,1,0] neg_lo:[1,0,0] neg_hi:[1,0,0]
	s_nop 0
	v_max_f32_e32 v1, 0, v1
	v_max_f32_e32 v0, 0, v0
	v_sqrt_f32_e32 v0, v0
	v_sqrt_f32_e32 v1, v1
	s_nop 0
	v_pk_mul_f32 v[0:1], v[2:3], v[0:1]
	s_nop 0
	v_pk_mul_f32 v[32:33], v[6:7], v[0:1]
	v_pk_add_f32 v[0:1], v[114:115], v[40:41]
	v_pk_add_f32 v[2:3], v[116:117], v[24:25]
	v_pk_mul_f32 v[0:1], v[0:1], s[14:15] op_sel_hi:[1,0]
	v_pk_mul_f32 v[2:3], v[2:3], s[14:15] op_sel_hi:[1,0]
	v_exp_f32_e32 v0, v0
	v_exp_f32_e32 v1, v1
	v_exp_f32_e32 v2, v2
	v_exp_f32_e32 v3, v3
	v_pk_add_f32 v[0:1], v[0:1], 1.0 op_sel_hi:[1,0]
	s_nop 0
	v_rcp_f32_e32 v0, v0
	v_rcp_f32_e32 v1, v1
	v_pk_add_f32 v[2:3], v[2:3], 1.0 op_sel_hi:[1,0]
	v_pk_mul_f32 v[0:1], v[124:125], v[0:1]
	s_nop 0
	v_exp_f32_e32 v40, v0
	v_exp_f32_e32 v41, v1
	v_rcp_f32_e32 v2, v2
	v_rcp_f32_e32 v3, v3
	v_pk_fma_f32 v[0:1], v[40:41], v[40:41], 1.0 op_sel_hi:[1,1,0] neg_lo:[1,0,0] neg_hi:[1,0,0]
	s_nop 0
	v_max_f32_e32 v1, 0, v1
	v_max_f32_e32 v0, 0, v0
	v_sqrt_f32_e32 v0, v0
	v_sqrt_f32_e32 v1, v1
	s_nop 0
	v_pk_mul_f32 v[0:1], v[2:3], v[0:1]
	s_nop 0
	v_pk_mul_f32 v[24:25], v[8:9], v[0:1]
	v_pk_add_f32 v[0:1], v[114:115], v[42:43]
	v_pk_add_f32 v[2:3], v[116:117], v[26:27]
	v_pk_mul_f32 v[0:1], v[0:1], s[14:15] op_sel_hi:[1,0]
	v_pk_mul_f32 v[2:3], v[2:3], s[14:15] op_sel_hi:[1,0]
	v_exp_f32_e32 v0, v0
	v_exp_f32_e32 v1, v1
	v_exp_f32_e32 v2, v2
	v_exp_f32_e32 v3, v3
	v_pk_add_f32 v[0:1], v[0:1], 1.0 op_sel_hi:[1,0]
	s_nop 0
	v_rcp_f32_e32 v0, v0
	v_rcp_f32_e32 v1, v1
	v_pk_add_f32 v[2:3], v[2:3], 1.0 op_sel_hi:[1,0]
	v_pk_mul_f32 v[0:1], v[124:125], v[0:1]
	s_nop 0
	v_exp_f32_e32 v42, v0
	v_exp_f32_e32 v43, v1
	v_rcp_f32_e32 v2, v2
	v_rcp_f32_e32 v3, v3
	v_pk_fma_f32 v[0:1], v[42:43], v[42:43], 1.0 op_sel_hi:[1,1,0] neg_lo:[1,0,0] neg_hi:[1,0,0]
	s_nop 0
	v_max_f32_e32 v1, 0, v1
	v_max_f32_e32 v0, 0, v0
	v_sqrt_f32_e32 v0, v0
	v_sqrt_f32_e32 v1, v1
	s_nop 0
	v_pk_mul_f32 v[0:1], v[2:3], v[0:1]
	s_nop 0
	v_pk_mul_f32 v[26:27], v[10:11], v[0:1]
	v_pk_add_f32 v[0:1], v[114:115], v[44:45]
	v_pk_add_f32 v[2:3], v[116:117], v[28:29]
	v_pk_mul_f32 v[0:1], v[0:1], s[14:15] op_sel_hi:[1,0]
	v_pk_mul_f32 v[2:3], v[2:3], s[14:15] op_sel_hi:[1,0]
	v_exp_f32_e32 v0, v0
	v_exp_f32_e32 v1, v1
	v_exp_f32_e32 v2, v2
	v_exp_f32_e32 v3, v3
	v_pk_add_f32 v[0:1], v[0:1], 1.0 op_sel_hi:[1,0]
	s_nop 0
	v_rcp_f32_e32 v0, v0
	v_rcp_f32_e32 v1, v1
	v_pk_add_f32 v[2:3], v[2:3], 1.0 op_sel_hi:[1,0]
	v_pk_mul_f32 v[0:1], v[124:125], v[0:1]
	s_nop 0
	v_exp_f32_e32 v44, v0
	v_exp_f32_e32 v45, v1
	v_rcp_f32_e32 v2, v2
	v_rcp_f32_e32 v3, v3
	v_pk_fma_f32 v[0:1], v[44:45], v[44:45], 1.0 op_sel_hi:[1,1,0] neg_lo:[1,0,0] neg_hi:[1,0,0]
	s_nop 0
	v_max_f32_e32 v1, 0, v1
	v_max_f32_e32 v0, 0, v0
	v_sqrt_f32_e32 v0, v0
	v_sqrt_f32_e32 v1, v1
	s_nop 0
	v_pk_mul_f32 v[0:1], v[2:3], v[0:1]
	s_nop 0
	v_pk_mul_f32 v[28:29], v[12:13], v[0:1]
	v_pk_add_f32 v[0:1], v[114:115], v[46:47]
	v_pk_add_f32 v[2:3], v[116:117], v[30:31]
	v_pk_mul_f32 v[0:1], v[0:1], s[14:15] op_sel_hi:[1,0]
	v_pk_mul_f32 v[2:3], v[2:3], s[14:15] op_sel_hi:[1,0]
	v_exp_f32_e32 v0, v0
	v_exp_f32_e32 v1, v1
	v_exp_f32_e32 v2, v2
	v_exp_f32_e32 v3, v3
	v_pk_add_f32 v[0:1], v[0:1], 1.0 op_sel_hi:[1,0]
	s_nop 0
	v_rcp_f32_e32 v0, v0
	v_rcp_f32_e32 v1, v1
	v_pk_add_f32 v[2:3], v[2:3], 1.0 op_sel_hi:[1,0]
	v_pk_mul_f32 v[0:1], v[124:125], v[0:1]
	s_nop 0
	v_exp_f32_e32 v46, v0
	v_exp_f32_e32 v47, v1
	v_rcp_f32_e32 v2, v2
	v_rcp_f32_e32 v3, v3
	v_pk_fma_f32 v[0:1], v[46:47], v[46:47], 1.0 op_sel_hi:[1,1,0] neg_lo:[1,0,0] neg_hi:[1,0,0]
	s_nop 0
	v_max_f32_e32 v1, 0, v1
	v_max_f32_e32 v0, 0, v0
	v_sqrt_f32_e32 v0, v0
	v_sqrt_f32_e32 v1, v1
	s_nop 0
	v_pk_mul_f32 v[0:1], v[2:3], v[0:1]
	s_nop 0
	v_pk_mul_f32 v[30:31], v[14:15], v[0:1]

; template <int DIR>
; __device__ __forceinline__ void lru_dir(const bf16_t* XR, const bf16_t* GATE, bf16_t* YP, u32x4* HSF, const bf16_t* bdw_dir, float bias_r, float bias_i, float sp,
;                                         int b, int n2, int lane, int wave, LAS float* xl) {
;     ...
;         for (int k = 0; k < 2; ++k) {
;             if (valid[k]) {
;                 const float val = Hl[k] + Pl[k] * hcar, got = __shfl_xor(val, 32);
;                 float hcur = first ? hcar : got;
;                 f32x16 hs;
; #pragma unroll
;                 for (int rr = 0; rr < 16; ++rr) { const int r = DIR == 0 ? rr : 15 - rr; hcur = av[k][r] * hcur + bv[k][r]; hs[r] = hcur; }
;                 const float got2 = __shfl_xor(hcur, 32);
;                 hcar = first ? got2 : hcur;
;                 const int tg = trow[k] < ML ? (trow[k] >> 12) * 136 + 8 + ((trow[k] & (SEQ - 1)) >> 5) : b * 136 + ((trow[k] - ML - b * CTXL) >> 5);
;                 u32x4* hp = HSF + (((size_t)tg * 32 + n2) * 64 + lane) * 2;
;                 if (DIR == 0) {
;                     u32x4 w0, w1;
;                     w0.x = pk2(hs[0], hs[1]); w0.y = pk2(hs[2], hs[3]); w0.z = pk2(hs[4], hs[5]); w0.w = pk2(hs[6], hs[7]);
;                     w1.x = pk2(hs[8], hs[9]); w1.y = pk2(hs[10], hs[11]); w1.z = pk2(hs[12], hs[13]); w1.w = pk2(hs[14], hs[15]);
;                     hp[0] = w0; hp[1] = w1;
;                 } else {
;                     const u32x4 w0 = hp[0], w1 = hp[1];
;                     const unsigned hw[8] = {w0.x, w0.y, w0.z, w0.w, w1.x, w1.y, w1.z, w1.w};
;                     const bf16_t* gp = GATE + (size_t)(trow[k] + tau) * DM + chcol + 8 * hh;
;                     const bf16x8 G0 = *(const bf16x8*)gp, G1 = *(const bf16x8*)(gp + 16);
;                     f32x16 gv;
; #pragma unroll
;                     for (int r = 0; r < 16; ++r) gv[r] = 0.f;
;                     gv = mfma32(G0, I0, gv); gv = mfma32(G1, I1, gv);
;                     bf16_t* yp = YP + (size_t)(trow[k] + 16 * hh) * DM + chcol + e;
; #pragma unroll
;                     for (int r = 0; r < 16; ++r) { const float x = gv[r], u2 = 1.5957691216f * (x + 0.044715f * x * x * x);
;                         const float hf = (r & 1) ? bfhi(hw[r >> 1]) : bflo(hw[r >> 1]);
;                         const float y = (hf + hs[r]) * x * sigmoidf_(u2);
;                         yp[(size_t)r * DM] = (bf16_t)f2bf(y); }
.LBB0_59:
	s_ashr_i32 s3, s2, 31
	s_lshl_b64 s[2:3], s[2:3], 16
	s_waitcnt lgkmcnt(0)
	v_cndmask_b32_e64 v170, v0, v138, s[40:41]
	v_lshl_add_u64 v[0:1], v[112:113], 0, s[2:3]
	s_waitcnt vmcnt(0)
	v_mov_b32_e32 v16, v184
	v_mov_b32_e32 v17, v185
	v_mov_b32_e32 v18, v186
	v_mov_b32_e32 v19, v187
	v_mov_b32_e32 v20, v188
	v_mov_b32_e32 v21, v189
	v_mov_b32_e32 v22, v190
	v_mov_b32_e32 v23, v191
	v_lshlrev_b64 v[0:1], 11, v[132:133]
	v_lshl_add_u64 v[4:5], v[120:121], 0, v[0:1]
	v_mov_b32_e32 v0, v192
	v_mov_b32_e32 v1, v193
	v_mov_b32_e32 v2, v194
	v_mov_b32_e32 v3, v195
	v_mov_b32_e32 v156, v196
	v_mov_b32_e32 v157, v197
	v_mov_b32_e32 v158, v198
	v_mov_b32_e32 v159, v199
	v_or_b32_e32 v98, s36, v102
	v_ashrrev_i32_e32 v99, 31, v98
	v_lshlrev_b64 v[98:99], 11, v[98:99]
	v_lshl_add_u64 v[98:99], v[122:123], 0, v[98:99]
	s_movk_i32 s2, 0x1000
	v_mfma_f32_32x32x16_bf16 v[0:15], v[0:3], v[58:61], 0
	v_lshlrev_b32_e32 v132, 16, v20
	v_add_f32_e32 v132, v138, v132
	v_and_b32_e32 v20, 0xffff0000, v20
	v_add_f32_e32 v20, v139, v20
	v_mfma_f32_32x32x16_bf16 v[0:15], v[156:159], v[62:65], v[0:15]
	s_nop 11
	v_mul_f32_e32 v111, 0x3d372713, v0
	v_mul_f32_e32 v111, v0, v111
	v_fma_f32 v111, v0, v111, v0
	v_mul_f32_e32 v111, 0x3fcc422a, v111
	v_mul_f32_e32 v111, 0xbfb8aa3b, v111
	v_exp_f32_e32 v111, v111
	v_mul_f32_e32 v0, v132, v0
	v_add_f32_e32 v111, 1.0, v111
	v_rcp_f32_e32 v111, v111
	s_nop 0
	v_mul_f32_e32 v0, v0, v111
	v_cvt_pk_bf16_f32 v0, v0, v49
	global_store_short v[98:99], v0, off
	v_mul_f32_e32 v0, 0x3d372713, v1
	v_mul_f32_e32 v0, v1, v0
	v_fma_f32 v0, v1, v0, v1
	v_mul_f32_e32 v0, 0x3fcc422a, v0
	v_mul_f32_e32 v0, 0xbfb8aa3b, v0
	v_exp_f32_e32 v0, v0
	v_mul_f32_e32 v1, v20, v1
	v_and_b32_e32 v20, 0xffff0000, v21
	v_add_f32_e32 v20, v135, v20
	v_add_f32_e32 v0, 1.0, v0
	v_rcp_f32_e32 v0, v0
	s_nop 0
	v_mul_f32_e32 v0, v1, v0
	v_cvt_pk_bf16_f32 v0, v0, v49
	global_store_short v[98:99], v0, off offset:2048
	v_mul_f32_e32 v0, 0x3d372713, v2
	v_mul_f32_e32 v0, v2, v0
	v_fma_f32 v0, v2, v0, v2
	v_mul_f32_e32 v0, 0x3fcc422a, v0
	v_mul_f32_e32 v0, 0xbfb8aa3b, v0
	v_exp_f32_e32 v0, v0
	v_lshlrev_b32_e32 v1, 16, v21
	v_add_f32_e32 v1, v134, v1
	v_mul_f32_e32 v1, v1, v2
	v_add_f32_e32 v0, 1.0, v0
	v_rcp_f32_e32 v0, v0
	s_nop 0
	v_mul_f32_e32 v0, v1, v0
	v_cvt_pk_bf16_f32 v2, v0, v49
	v_add_co_u32_e32 v0, vcc, s2, v98
	s_movk_i32 s2, 0x3000
	s_nop 0
	v_addc_co_u32_e32 v1, vcc, 0, v99, vcc
	v_add_co_u32_e32 v132, vcc, s76, v98
	s_nop 1
	v_addc_co_u32_e32 v133, vcc, 0, v99, vcc
	global_store_short v[132:133], v2, off offset:-4096
	v_mul_f32_e32 v2, 0x3d372713, v3
	v_mul_f32_e32 v2, v3, v2
	v_fma_f32 v2, v3, v2, v3
	v_mul_f32_e32 v2, 0x3fcc422a, v2
	v_mul_f32_e32 v2, 0xbfb8aa3b, v2
	v_exp_f32_e32 v2, v2
	v_mul_f32_e32 v3, v20, v3
	v_add_f32_e32 v2, 1.0, v2
	v_rcp_f32_e32 v2, v2
	s_nop 0
	v_mul_f32_e32 v2, v3, v2
	v_cvt_pk_bf16_f32 v2, v2, v49
	global_store_short v[0:1], v2, off offset:2048
	v_mul_f32_e32 v0, 0x3d372713, v4
	v_mul_f32_e32 v0, v4, v0
	v_fma_f32 v0, v4, v0, v4
	v_mul_f32_e32 v0, 0x3fcc422a, v0
	v_mul_f32_e32 v0, 0xbfb8aa3b, v0
	v_exp_f32_e32 v0, v0
	v_lshlrev_b32_e32 v1, 16, v22
	v_add_f32_e32 v1, v136, v1
	v_mul_f32_e32 v1, v1, v4
	v_add_f32_e32 v0, 1.0, v0
	v_rcp_f32_e32 v0, v0
	s_nop 0
	v_mul_f32_e32 v0, v1, v0
	v_cvt_pk_bf16_f32 v0, v0, v49
	global_store_short v[132:133], v0, off
	v_mul_f32_e32 v0, 0x3d372713, v5
	v_mul_f32_e32 v0, v5, v0
	v_fma_f32 v0, v5, v0, v5
	v_mul_f32_e32 v0, 0x3fcc422a, v0
	v_mul_f32_e32 v0, 0xbfb8aa3b, v0
	v_exp_f32_e32 v0, v0
	v_and_b32_e32 v1, 0xffff0000, v22
	v_add_f32_e32 v1, v137, v1
	v_mul_f32_e32 v1, v1, v5
	v_add_f32_e32 v0, 1.0, v0
	v_rcp_f32_e32 v0, v0
	v_and_b32_e32 v5, 0xffff0000, v23
	v_add_f32_e32 v5, v129, v5
	v_mul_f32_e32 v5, v5, v7
	v_mul_f32_e32 v0, v1, v0
	v_cvt_pk_bf16_f32 v0, v0, v49
	global_store_short v[132:133], v0, off offset:2048
	v_mul_f32_e32 v0, 0x3d372713, v6
	v_mul_f32_e32 v0, v6, v0
	v_fma_f32 v0, v6, v0, v6
	v_mul_f32_e32 v0, 0x3fcc422a, v0
	v_mul_f32_e32 v0, 0xbfb8aa3b, v0
	v_exp_f32_e32 v0, v0
	v_lshlrev_b32_e32 v1, 16, v23
	v_add_f32_e32 v1, v128, v1
	v_mul_f32_e32 v1, v1, v6
	v_add_f32_e32 v0, 1.0, v0
	v_rcp_f32_e32 v0, v0
	s_nop 0
	v_mul_f32_e32 v0, v1, v0
	v_cvt_pk_bf16_f32 v4, v0, v49
	v_add_co_u32_e32 v0, vcc, s2, v98
; __device__ __forceinline__ unsigned f2bf(float f) { return pk2(f, 0.0f) & 0xffffu; }
; __device__ __forceinline__ float bflo(unsigned w) { return __uint_as_float(w << 16); }
; __device__ __forceinline__ float bfhi(unsigned w) { return __uint_as_float(w & 0xffff0000u); }
; __device__ __forceinline__ float sigmoidf_(float x) { return __builtin_amdgcn_rcpf(1.0f + __builtin_amdgcn_exp2f(x * -1.4426950408889634f)); }
; template <int DIR>
; __device__ __forceinline__ void lru_dir(const bf16_t* XR, const bf16_t* GATE, bf16_t* YP, u32x4* HSF, const bf16_t* bdw_dir, float bias_r, float bias_i, float sp,
;                                         int b, int n2, int lane, int wave, LAS float* xl) {
;     ...
;                     bf16_t* yp = YP + (size_t)(trow[k] + 16 * hh) * DM + chcol + e;
; #pragma unroll
;                     for (int r = 0; r < 16; ++r) { const float x = gv[r], u2 = 1.5957691216f * (x + 0.044715f * x * x * x);
;                         const float hf = (r & 1) ? bfhi(hw[r >> 1]) : bflo(hw[r >> 1]);
;                         const float y = (hf + hs[r]) * x * sigmoidf_(u2);
;                         yp[(size_t)r * DM] = (bf16_t)f2bf(y); }
	s_movk_i32 s2, 0x4000
	s_nop 0
	v_addc_co_u32_e32 v1, vcc, 0, v99, vcc
	v_add_co_u32_e32 v2, vcc, s2, v98
	s_movk_i32 s2, 0x5000
	s_nop 0
	v_addc_co_u32_e32 v3, vcc, 0, v99, vcc
	global_store_short v[2:3], v4, off offset:-4096
	v_mul_f32_e32 v4, 0x3d372713, v7
	v_mul_f32_e32 v4, v7, v4
	v_fma_f32 v4, v7, v4, v7
	v_mul_f32_e32 v4, 0x3fcc422a, v4
	v_mul_f32_e32 v4, 0xbfb8aa3b, v4
	v_exp_f32_e32 v4, v4
	s_nop 0
	v_add_f32_e32 v4, 1.0, v4
	v_rcp_f32_e32 v4, v4
	s_nop 0
	v_mul_f32_e32 v4, v5, v4
	v_cvt_pk_bf16_f32 v4, v4, v49
	global_store_short v[0:1], v4, off offset:2048
	v_mul_f32_e32 v0, 0x3d372713, v8
	v_mul_f32_e32 v0, v8, v0
	v_fma_f32 v0, v8, v0, v8
	v_mul_f32_e32 v0, 0x3fcc422a, v0
	v_mul_f32_e32 v0, 0xbfb8aa3b, v0
	v_exp_f32_e32 v0, v0
	v_lshlrev_b32_e32 v1, 16, v16
	v_add_f32_e32 v1, v130, v1
	v_mul_f32_e32 v1, v1, v8
	v_add_f32_e32 v0, 1.0, v0
	v_rcp_f32_e32 v0, v0
	v_and_b32_e32 v5, 0xffff0000, v17
	v_add_f32_e32 v5, v147, v5
	v_mul_f32_e32 v5, v5, v11
	v_mul_f32_e32 v0, v1, v0
	v_cvt_pk_bf16_f32 v0, v0, v49
	global_store_short v[2:3], v0, off
	v_mul_f32_e32 v0, 0x3d372713, v9
	v_mul_f32_e32 v0, v9, v0
	v_fma_f32 v0, v9, v0, v9
	v_mul_f32_e32 v0, 0x3fcc422a, v0
	v_mul_f32_e32 v0, 0xbfb8aa3b, v0
	v_exp_f32_e32 v0, v0
	v_and_b32_e32 v1, 0xffff0000, v16
	v_add_f32_e32 v1, v131, v1
	v_mul_f32_e32 v1, v1, v9
	v_add_f32_e32 v0, 1.0, v0
	v_rcp_f32_e32 v0, v0
	s_nop 0
	v_mul_f32_e32 v0, v1, v0
	v_cvt_pk_bf16_f32 v0, v0, v49
	global_store_short v[2:3], v0, off offset:2048
	v_mul_f32_e32 v0, 0x3d372713, v10
	v_mul_f32_e32 v0, v10, v0
	v_fma_f32 v0, v10, v0, v10
	v_mul_f32_e32 v0, 0x3fcc422a, v0
	v_mul_f32_e32 v0, 0xbfb8aa3b, v0
	v_exp_f32_e32 v0, v0
	v_lshlrev_b32_e32 v1, 16, v17
	v_add_f32_e32 v1, v146, v1
	v_mul_f32_e32 v1, v1, v10
	v_add_f32_e32 v0, 1.0, v0
	v_rcp_f32_e32 v0, v0
	s_nop 0
	v_mul_f32_e32 v0, v1, v0
	v_cvt_pk_bf16_f32 v4, v0, v49
	v_add_co_u32_e32 v0, vcc, s2, v98
	s_movk_i32 s2, 0x7000
	s_nop 0
	v_addc_co_u32_e32 v1, vcc, 0, v99, vcc
	v_add_co_u32_e32 v2, vcc, s4, v98
	s_nop 1
	v_addc_co_u32_e32 v3, vcc, 0, v99, vcc
	global_store_short v[2:3], v4, off offset:-4096
	v_mul_f32_e32 v4, 0x3d372713, v11
	v_mul_f32_e32 v4, v11, v4
	v_fma_f32 v4, v11, v4, v11
	v_mul_f32_e32 v4, 0x3fcc422a, v4
	v_mul_f32_e32 v4, 0xbfb8aa3b, v4
	v_exp_f32_e32 v4, v4
	s_nop 0
	v_add_f32_e32 v4, 1.0, v4
	v_rcp_f32_e32 v4, v4
	s_nop 0
	v_mul_f32_e32 v4, v5, v4
	v_cvt_pk_bf16_f32 v4, v4, v49
	global_store_short v[0:1], v4, off offset:2048
	v_mul_f32_e32 v0, 0x3d372713, v12
	v_mul_f32_e32 v0, v12, v0
	v_fma_f32 v0, v12, v0, v12
	v_mul_f32_e32 v0, 0x3fcc422a, v0
	v_mul_f32_e32 v0, 0xbfb8aa3b, v0
	v_exp_f32_e32 v0, v0
	v_lshlrev_b32_e32 v1, 16, v18
	v_add_f32_e32 v1, v148, v1
	v_mul_f32_e32 v1, v1, v12
	v_add_f32_e32 v0, 1.0, v0
	v_rcp_f32_e32 v0, v0
	s_nop 0
	v_mul_f32_e32 v0, v1, v0
	v_cvt_pk_bf16_f32 v0, v0, v49
	global_store_short v[2:3], v0, off
	v_mul_f32_e32 v0, 0x3d372713, v13
	v_mul_f32_e32 v0, v13, v0
	v_fma_f32 v0, v13, v0, v13
	v_mul_f32_e32 v0, 0x3fcc422a, v0
	v_mul_f32_e32 v0, 0xbfb8aa3b, v0
	v_exp_f32_e32 v0, v0
	v_and_b32_e32 v1, 0xffff0000, v18
	v_add_f32_e32 v1, v149, v1
	v_mul_f32_e32 v1, v1, v13
	v_add_f32_e32 v0, 1.0, v0
	v_rcp_f32_e32 v0, v0
	s_nop 0
	v_mul_f32_e32 v0, v1, v0
	v_cvt_pk_bf16_f32 v0, v0, v49
	global_store_short v[2:3], v0, off offset:2048
	v_mul_f32_e32 v0, 0x3d372713, v14
	v_mul_f32_e32 v0, v14, v0
	v_fma_f32 v0, v14, v0, v14
	v_mul_f32_e32 v0, 0x3fcc422a, v0
	v_mul_f32_e32 v0, 0xbfb8aa3b, v0
	v_exp_f32_e32 v0, v0
	v_lshlrev_b32_e32 v1, 16, v19
	v_add_f32_e32 v1, v150, v1
	v_mul_f32_e32 v1, v1, v14
	v_add_f32_e32 v0, 1.0, v0
	v_rcp_f32_e32 v0, v0
	v_and_b32_e32 v3, 0xffff0000, v19
	v_add_f32_e32 v3, v151, v3
	v_mul_f32_e32 v3, v3, v15
	v_mul_f32_e32 v0, v1, v0
	v_cvt_pk_bf16_f32 v2, v0, v49
	v_add_co_u32_e32 v0, vcc, s2, v98
	s_nop 1
	v_addc_co_u32_e32 v1, vcc, 0, v99, vcc
	global_store_short v[0:1], v2, off
	v_mul_f32_e32 v2, 0x3d372713, v15
	v_mul_f32_e32 v2, v15, v2
	v_fma_f32 v2, v15, v2, v15
	v_mul_f32_e32 v2, 0x3fcc422a, v2
	v_mul_f32_e32 v2, 0xbfb8aa3b, v2
	v_exp_f32_e32 v2, v2
	s_nop 0
	v_add_f32_e32 v2, 1.0, v2
	v_rcp_f32_e32 v2, v2
	s_nop 0
	v_mul_f32_e32 v2, v3, v2
	v_cvt_pk_bf16_f32 v2, v2, v49
	global_store_short v[0:1], v2, off offset:2048
